# attention loop: softmax row sums accumulated with v_pk_add_f32 (32 packed adds per tile instead of 64 scalar), same per-chain order
# speedup vs baseline: 1.0077x; 1.0077x over previous
; template <int DQK>
; DI void attn_item(const bf16_t* __restrict__ Q, const bf16_t* __restrict__ Kp, const bf16_t* __restrict__ Vt, int q0, int nkeys,
;                   bf16_t* __restrict__ mix, int colbase, int b, char* smem) {
;     ...
;   const int nt = nkeys >> 6;
;   A_LOAD(p, 0)
;   A_LOAD(q, 64)
;   A_WRITE(p, 0)
;   __syncthreads();
;   if (nt > 2) A_LOAD(p, 128)
;   for (int kt = 0; kt < nt; kt += 2) {
;     A_TILE(0)
;     A_WRITE(q, 1)
;     __syncthreads();
;     if (kt + 3 < nt) A_LOAD(q, (kt + 3) << 6)
;     A_TILE(1)
;     if (kt + 2 < nt) A_WRITE(p, 0)
;     __syncthreads();
;     if (kt + 4 < nt) A_LOAD(p, (kt + 4) << 6)
;   }
.Lat2_loop_g:
	s_waitcnt vmcnt(0)
	ds_write_b128 v131, v[224:227] offset:9216
	ds_write_b128 v132, v[228:231] offset:9216
	ds_write_b64 v134, v[236:237] offset:27136
	ds_write_b64 v134, v[238:239] offset:27144
	ds_write_b64 v135, v[240:241] offset:27136
	ds_write_b64 v135, v[242:243] offset:27144
	s_add_u32 s1, s68, 2
	s_min_u32 s0, s1, 67
	s_mul_i32 s10, s0, 0x2000
	s_add_u32 s64, s60, s10
	s_addc_u32 s65, s61, 0
	s_lshl_b32 s0, s0, 7
	s_add_u32 s66, s62, s0
	s_addc_u32 s67, s63, 0
	global_load_dwordx4 v[224:227], v136, s[64:65]
	global_load_dwordx4 v[228:231], v137, s[64:65]
	global_load_dwordx4 v[236:239], v139, s[66:67]
	global_load_dwordx4 v[240:243], v140, s[66:67]
	v_add_u32_e32 v248, 0x4800, v129
	v_add_u32_e32 v249, 0x4800, v130
	ds_read2_b64 v[192:195], v248 offset0:0 offset1:2
	ds_read2_b64 v[196:199], v249 offset0:0 offset1:2
	ds_read2_b64 v[200:203], v248 offset0:4 offset1:6
	ds_read2_b64 v[204:207], v249 offset0:4 offset1:6
	v_exp_f32_e32 v64, v64
	v_exp_f32_e32 v65, v65
	v_exp_f32_e32 v66, v66
	v_exp_f32_e32 v67, v67
	v_exp_f32_e32 v68, v68
	v_exp_f32_e32 v69, v69
	v_exp_f32_e32 v70, v70
	v_exp_f32_e32 v71, v71
	v_exp_f32_e32 v96, v96
	v_exp_f32_e32 v97, v97
	v_exp_f32_e32 v98, v98
	v_exp_f32_e32 v99, v99
	v_exp_f32_e32 v100, v100
	v_exp_f32_e32 v101, v101
	v_exp_f32_e32 v102, v102
	v_exp_f32_e32 v103, v103
	v_pk_add_f32 v[244:245], v[244:245], v[64:65]
	v_pk_add_f32 v[246:247], v[246:247], v[96:97]
	v_pk_add_f32 v[244:245], v[244:245], v[66:67]
	v_pk_add_f32 v[246:247], v[246:247], v[98:99]
	v_pk_add_f32 v[244:245], v[244:245], v[68:69]
	v_pk_add_f32 v[246:247], v[246:247], v[100:101]
	v_pk_add_f32 v[244:245], v[244:245], v[70:71]
	v_pk_add_f32 v[246:247], v[246:247], v[102:103]
	v_cvt_pk_bf16_f32 v64, v64, v65
	v_cvt_pk_bf16_f32 v65, v66, v67
	v_cvt_pk_bf16_f32 v66, v68, v69
	v_cvt_pk_bf16_f32 v67, v70, v71
	v_cvt_pk_bf16_f32 v96, v96, v97
	v_cvt_pk_bf16_f32 v97, v98, v99
	v_cvt_pk_bf16_f32 v98, v100, v101
	v_cvt_pk_bf16_f32 v99, v102, v103
	s_waitcnt lgkmcnt(3)
	v_mfma_f32_32x32x16_bf16 v[0:15], v[192:195], v[64:67], v[0:15]
	v_mfma_f32_32x32x16_bf16 v[32:47], v[192:195], v[96:99], v[32:47]
	ds_read2_b64 v[192:195], v248 offset0:8 offset1:10
	s_waitcnt lgkmcnt(3)
	v_mfma_f32_32x32x16_bf16 v[16:31], v[196:199], v[64:67], v[16:31]
	v_mfma_f32_32x32x16_bf16 v[48:63], v[196:199], v[96:99], v[48:63]
	ds_read2_b64 v[196:199], v249 offset0:8 offset1:10
	v_exp_f32_e32 v72, v72
	v_exp_f32_e32 v73, v73
	v_exp_f32_e32 v74, v74
	v_exp_f32_e32 v75, v75
	v_exp_f32_e32 v76, v76
	v_exp_f32_e32 v77, v77
	v_exp_f32_e32 v78, v78
	v_exp_f32_e32 v79, v79
	v_exp_f32_e32 v104, v104
	v_exp_f32_e32 v105, v105
	v_exp_f32_e32 v106, v106
	v_exp_f32_e32 v107, v107
	v_exp_f32_e32 v108, v108
	v_exp_f32_e32 v109, v109
	v_exp_f32_e32 v110, v110
	v_exp_f32_e32 v111, v111
	v_pk_add_f32 v[244:245], v[244:245], v[72:73]
	v_pk_add_f32 v[246:247], v[246:247], v[104:105]
	v_pk_add_f32 v[244:245], v[244:245], v[74:75]
	v_pk_add_f32 v[246:247], v[246:247], v[106:107]
	v_pk_add_f32 v[244:245], v[244:245], v[76:77]
	v_pk_add_f32 v[246:247], v[246:247], v[108:109]
	v_pk_add_f32 v[244:245], v[244:245], v[78:79]
	v_pk_add_f32 v[246:247], v[246:247], v[110:111]
	v_cvt_pk_bf16_f32 v68, v72, v73
	v_cvt_pk_bf16_f32 v69, v74, v75
	v_cvt_pk_bf16_f32 v70, v76, v77
	v_cvt_pk_bf16_f32 v71, v78, v79
	v_cvt_pk_bf16_f32 v100, v104, v105
	v_cvt_pk_bf16_f32 v101, v106, v107
	v_cvt_pk_bf16_f32 v102, v108, v109
	v_cvt_pk_bf16_f32 v103, v110, v111
	s_waitcnt lgkmcnt(3)
	v_mfma_f32_32x32x16_bf16 v[0:15], v[200:203], v[68:71], v[0:15]
	v_mfma_f32_32x32x16_bf16 v[32:47], v[200:203], v[100:103], v[32:47]
	ds_read2_b64 v[200:203], v248 offset0:12 offset1:14
	s_waitcnt lgkmcnt(3)
	v_mfma_f32_32x32x16_bf16 v[16:31], v[204:207], v[68:71], v[16:31]
	v_mfma_f32_32x32x16_bf16 v[48:63], v[204:207], v[100:103], v[48:63]
	ds_read2_b64 v[204:207], v249 offset0:12 offset1:14
	v_exp_f32_e32 v80, v80
	v_exp_f32_e32 v81, v81
	v_exp_f32_e32 v82, v82
	v_exp_f32_e32 v83, v83
	v_exp_f32_e32 v84, v84
	v_exp_f32_e32 v85, v85
	v_exp_f32_e32 v86, v86
	v_exp_f32_e32 v87, v87
	v_exp_f32_e32 v112, v112
	v_exp_f32_e32 v113, v113
	v_exp_f32_e32 v114, v114
	v_exp_f32_e32 v115, v115
	v_exp_f32_e32 v116, v116
	v_exp_f32_e32 v117, v117
	v_exp_f32_e32 v118, v118
	v_exp_f32_e32 v119, v119
	v_pk_add_f32 v[244:245], v[244:245], v[80:81]
	v_pk_add_f32 v[246:247], v[246:247], v[112:113]
	v_pk_add_f32 v[244:245], v[244:245], v[82:83]
	v_pk_add_f32 v[246:247], v[246:247], v[114:115]
	v_pk_add_f32 v[244:245], v[244:245], v[84:85]
	v_pk_add_f32 v[246:247], v[246:247], v[116:117]
	v_pk_add_f32 v[244:245], v[244:245], v[86:87]
	v_pk_add_f32 v[246:247], v[246:247], v[118:119]
	v_cvt_pk_bf16_f32 v72, v80, v81
	v_cvt_pk_bf16_f32 v73, v82, v83
	v_cvt_pk_bf16_f32 v74, v84, v85
	v_cvt_pk_bf16_f32 v75, v86, v87
	v_cvt_pk_bf16_f32 v104, v112, v113
	v_cvt_pk_bf16_f32 v105, v114, v115
	v_cvt_pk_bf16_f32 v106, v116, v117
	v_cvt_pk_bf16_f32 v107, v118, v119
	s_waitcnt lgkmcnt(3)
	v_mfma_f32_32x32x16_bf16 v[0:15], v[192:195], v[72:75], v[0:15]
	v_mfma_f32_32x32x16_bf16 v[32:47], v[192:195], v[104:107], v[32:47]
	s_waitcnt lgkmcnt(2)
	v_mfma_f32_32x32x16_bf16 v[16:31], v[196:199], v[72:75], v[16:31]
	v_mfma_f32_32x32x16_bf16 v[48:63], v[196:199], v[104:107], v[48:63]
	v_exp_f32_e32 v88, v88
	v_exp_f32_e32 v89, v89
	v_exp_f32_e32 v90, v90
	v_exp_f32_e32 v91, v91
	v_exp_f32_e32 v92, v92
	v_exp_f32_e32 v93, v93
	v_exp_f32_e32 v94, v94
	v_exp_f32_e32 v95, v95
	v_exp_f32_e32 v120, v120
	v_exp_f32_e32 v121, v121
	v_exp_f32_e32 v122, v122
	v_exp_f32_e32 v123, v123
	v_exp_f32_e32 v124, v124
	v_exp_f32_e32 v125, v125
	v_exp_f32_e32 v126, v126
	v_exp_f32_e32 v127, v127
	v_pk_add_f32 v[244:245], v[244:245], v[88:89]
	v_pk_add_f32 v[246:247], v[246:247], v[120:121]
	v_pk_add_f32 v[244:245], v[244:245], v[90:91]
	v_pk_add_f32 v[246:247], v[246:247], v[122:123]
	v_pk_add_f32 v[244:245], v[244:245], v[92:93]
	v_pk_add_f32 v[246:247], v[246:247], v[124:125]
	v_pk_add_f32 v[244:245], v[244:245], v[94:95]
	v_pk_add_f32 v[246:247], v[246:247], v[126:127]
	v_cvt_pk_bf16_f32 v76, v88, v89
	v_cvt_pk_bf16_f32 v77, v90, v91
	v_cvt_pk_bf16_f32 v78, v92, v93
	v_cvt_pk_bf16_f32 v79, v94, v95
	v_cvt_pk_bf16_f32 v108, v120, v121
	v_cvt_pk_bf16_f32 v109, v122, v123
	v_cvt_pk_bf16_f32 v110, v124, v125
	v_cvt_pk_bf16_f32 v111, v126, v127
	s_waitcnt lgkmcnt(1)
	v_mfma_f32_32x32x16_bf16 v[0:15], v[200:203], v[76:79], v[0:15]
	v_mfma_f32_32x32x16_bf16 v[32:47], v[200:203], v[108:111], v[32:47]
	s_waitcnt lgkmcnt(0)
	v_mfma_f32_32x32x16_bf16 v[16:31], v[204:207], v[76:79], v[16:31]
	v_mfma_f32_32x32x16_bf16 v[48:63], v[204:207], v[108:111], v[48:63]
	s_add_u32 s68, s68, 1
	s_waitcnt lgkmcnt(0)
	s_barrier
; template <int DQK>
; DI void attn_item(const bf16_t* __restrict__ Q, const bf16_t* __restrict__ Kp, const bf16_t* __restrict__ Vt, int q0, int nkeys,
;                   bf16_t* __restrict__ mix, int colbase, int b, char* smem) {
;     ...
;   const int nt = nkeys >> 6;
;   A_LOAD(p, 0)
;   A_LOAD(q, 64)
;   A_WRITE(p, 0)
;   __syncthreads();
;   if (nt > 2) A_LOAD(p, 128)
;   for (int kt = 0; kt < nt; kt += 2) {
;     A_TILE(0)
;     A_WRITE(q, 1)
;     __syncthreads();
;     if (kt + 3 < nt) A_LOAD(q, (kt + 3) << 6)
;     A_TILE(1)
;     if (kt + 2 < nt) A_WRITE(p, 0)
;     __syncthreads();
;     if (kt + 4 < nt) A_LOAD(p, (kt + 4) << 6)
	ds_read_b128 v[192:195], v128 offset:9216
	ds_read_b128 v[196:199], v128 offset:13824
	ds_read_b128 v[200:203], v128 offset:9248
	ds_read_b128 v[204:207], v128 offset:13856
	s_waitcnt lgkmcnt(3)
	v_mfma_f32_32x32x16_bf16 v[64:79], v[192:195], v[144:147], v[208:223]
	v_mfma_f32_32x32x16_bf16 v[96:111], v[192:195], v[168:171], v[208:223]
	ds_read_b128 v[192:195], v128 offset:9280
	s_waitcnt lgkmcnt(3)
	v_mfma_f32_32x32x16_bf16 v[80:95], v[196:199], v[144:147], v[208:223]
	v_mfma_f32_32x32x16_bf16 v[112:127], v[196:199], v[168:171], v[208:223]
	ds_read_b128 v[196:199], v128 offset:13888
	s_waitcnt lgkmcnt(3)
	v_mfma_f32_32x32x16_bf16 v[64:79], v[200:203], v[148:151], v[64:79]
	v_mfma_f32_32x32x16_bf16 v[96:111], v[200:203], v[172:175], v[96:111]
	ds_read_b128 v[200:203], v128 offset:9312
	s_waitcnt lgkmcnt(3)
	v_mfma_f32_32x32x16_bf16 v[80:95], v[204:207], v[148:151], v[80:95]
	v_mfma_f32_32x32x16_bf16 v[112:127], v[204:207], v[172:175], v[112:127]
	ds_read_b128 v[204:207], v128 offset:13920
	s_waitcnt lgkmcnt(3)
	v_mfma_f32_32x32x16_bf16 v[64:79], v[192:195], v[152:155], v[64:79]
	v_mfma_f32_32x32x16_bf16 v[96:111], v[192:195], v[176:179], v[96:111]
	s_waitcnt lgkmcnt(2)
	v_mfma_f32_32x32x16_bf16 v[80:95], v[196:199], v[152:155], v[80:95]
	v_mfma_f32_32x32x16_bf16 v[112:127], v[196:199], v[176:179], v[112:127]
	s_waitcnt lgkmcnt(1)
	v_mfma_f32_32x32x16_bf16 v[64:79], v[200:203], v[156:159], v[64:79]
	v_mfma_f32_32x32x16_bf16 v[96:111], v[200:203], v[180:183], v[96:111]
	s_waitcnt lgkmcnt(0)
	v_mfma_f32_32x32x16_bf16 v[80:95], v[204:207], v[156:159], v[80:95]
	v_mfma_f32_32x32x16_bf16 v[112:127], v[204:207], v[180:183], v[112:127]
	s_waitcnt vmcnt(0)
	ds_write_b128 v131, v[224:227] offset:0
	ds_write_b128 v132, v[228:231] offset:0
	ds_write_b64 v134, v[236:237] offset:18432
	ds_write_b64 v134, v[238:239] offset:18440
	ds_write_b64 v135, v[240:241] offset:18432
	ds_write_b64 v135, v[242:243] offset:18440
	s_add_u32 s1, s68, 2
	s_min_u32 s0, s1, 67
	s_mul_i32 s10, s0, 0x2000
	s_add_u32 s64, s60, s10
	s_addc_u32 s65, s61, 0
	s_lshl_b32 s0, s0, 7
	s_add_u32 s66, s62, s0
	s_addc_u32 s67, s63, 0
	global_load_dwordx4 v[224:227], v136, s[64:65]
	global_load_dwordx4 v[228:231], v137, s[64:65]
	global_load_dwordx4 v[236:239], v139, s[66:67]
	global_load_dwordx4 v[240:243], v140, s[66:67]
	v_add_u32_e32 v248, 0x6a00, v129
	v_add_u32_e32 v249, 0x6a00, v130
	ds_read2_b64 v[192:195], v248 offset0:0 offset1:2
	ds_read2_b64 v[196:199], v249 offset0:0 offset1:2
	ds_read2_b64 v[200:203], v248 offset0:4 offset1:6
	ds_read2_b64 v[204:207], v249 offset0:4 offset1:6
	v_exp_f32_e32 v64, v64
	v_exp_f32_e32 v65, v65
	v_exp_f32_e32 v66, v66
	v_exp_f32_e32 v67, v67
	v_exp_f32_e32 v68, v68
	v_exp_f32_e32 v69, v69
	v_exp_f32_e32 v70, v70
	v_exp_f32_e32 v71, v71
	v_exp_f32_e32 v96, v96
	v_exp_f32_e32 v97, v97
	v_exp_f32_e32 v98, v98
	v_exp_f32_e32 v99, v99
	v_exp_f32_e32 v100, v100
	v_exp_f32_e32 v101, v101
	v_exp_f32_e32 v102, v102
	v_exp_f32_e32 v103, v103
	v_pk_add_f32 v[244:245], v[244:245], v[64:65]
	v_pk_add_f32 v[246:247], v[246:247], v[96:97]
	v_pk_add_f32 v[244:245], v[244:245], v[66:67]
	v_pk_add_f32 v[246:247], v[246:247], v[98:99]
	v_pk_add_f32 v[244:245], v[244:245], v[68:69]
	v_pk_add_f32 v[246:247], v[246:247], v[100:101]
	v_pk_add_f32 v[244:245], v[244:245], v[70:71]
	v_pk_add_f32 v[246:247], v[246:247], v[102:103]
	v_cvt_pk_bf16_f32 v64, v64, v65
	v_cvt_pk_bf16_f32 v65, v66, v67
	v_cvt_pk_bf16_f32 v66, v68, v69
	v_cvt_pk_bf16_f32 v67, v70, v71
	v_cvt_pk_bf16_f32 v96, v96, v97
	v_cvt_pk_bf16_f32 v97, v98, v99
	v_cvt_pk_bf16_f32 v98, v100, v101
	v_cvt_pk_bf16_f32 v99, v102, v103
	s_waitcnt lgkmcnt(3)
	v_mfma_f32_32x32x16_bf16 v[0:15], v[192:195], v[64:67], v[0:15]
	v_mfma_f32_32x32x16_bf16 v[32:47], v[192:195], v[96:99], v[32:47]
	ds_read2_b64 v[192:195], v248 offset0:8 offset1:10
	s_waitcnt lgkmcnt(3)
	v_mfma_f32_32x32x16_bf16 v[16:31], v[196:199], v[64:67], v[16:31]
	v_mfma_f32_32x32x16_bf16 v[48:63], v[196:199], v[96:99], v[48:63]
	ds_read2_b64 v[196:199], v249 offset0:8 offset1:10
	v_exp_f32_e32 v72, v72
	v_exp_f32_e32 v73, v73
	v_exp_f32_e32 v74, v74
	v_exp_f32_e32 v75, v75
	v_exp_f32_e32 v76, v76
	v_exp_f32_e32 v77, v77
	v_exp_f32_e32 v78, v78
	v_exp_f32_e32 v79, v79
	v_exp_f32_e32 v104, v104
	v_exp_f32_e32 v105, v105
	v_exp_f32_e32 v106, v106
	v_exp_f32_e32 v107, v107
	v_exp_f32_e32 v108, v108
	v_exp_f32_e32 v109, v109
	v_exp_f32_e32 v110, v110
	v_exp_f32_e32 v111, v111
	v_pk_add_f32 v[244:245], v[244:245], v[72:73]
	v_pk_add_f32 v[246:247], v[246:247], v[104:105]
	v_pk_add_f32 v[244:245], v[244:245], v[74:75]
	v_pk_add_f32 v[246:247], v[246:247], v[106:107]
	v_pk_add_f32 v[244:245], v[244:245], v[76:77]
	v_pk_add_f32 v[246:247], v[246:247], v[108:109]
	v_pk_add_f32 v[244:245], v[244:245], v[78:79]
	v_pk_add_f32 v[246:247], v[246:247], v[110:111]
	v_cvt_pk_bf16_f32 v68, v72, v73
	v_cvt_pk_bf16_f32 v69, v74, v75
	v_cvt_pk_bf16_f32 v70, v76, v77
	v_cvt_pk_bf16_f32 v71, v78, v79
	v_cvt_pk_bf16_f32 v100, v104, v105
	v_cvt_pk_bf16_f32 v101, v106, v107
	v_cvt_pk_bf16_f32 v102, v108, v109
	v_cvt_pk_bf16_f32 v103, v110, v111
	s_waitcnt lgkmcnt(3)
	v_mfma_f32_32x32x16_bf16 v[0:15], v[200:203], v[68:71], v[0:15]
	v_mfma_f32_32x32x16_bf16 v[32:47], v[200:203], v[100:103], v[32:47]
	ds_read2_b64 v[200:203], v248 offset0:12 offset1:14
	s_waitcnt lgkmcnt(3)
; template <int DQK>
; DI void attn_item(const bf16_t* __restrict__ Q, const bf16_t* __restrict__ Kp, const bf16_t* __restrict__ Vt, int q0, int nkeys,
;                   bf16_t* __restrict__ mix, int colbase, int b, char* smem) {
;     ...
;   const int nt = nkeys >> 6;
;   A_LOAD(p, 0)
;   A_LOAD(q, 64)
;   A_WRITE(p, 0)
;   __syncthreads();
;   if (nt > 2) A_LOAD(p, 128)
;   for (int kt = 0; kt < nt; kt += 2) {
;     A_TILE(0)
;     A_WRITE(q, 1)
;     __syncthreads();
;     if (kt + 3 < nt) A_LOAD(q, (kt + 3) << 6)
;     A_TILE(1)
;     if (kt + 2 < nt) A_WRITE(p, 0)
;     __syncthreads();
;     if (kt + 4 < nt) A_LOAD(p, (kt + 4) << 6)
	v_mfma_f32_32x32x16_bf16 v[16:31], v[204:207], v[68:71], v[16:31]
	v_mfma_f32_32x32x16_bf16 v[48:63], v[204:207], v[100:103], v[48:63]
	ds_read2_b64 v[204:207], v249 offset0:12 offset1:14
	v_exp_f32_e32 v80, v80
	v_exp_f32_e32 v81, v81
	v_exp_f32_e32 v82, v82
	v_exp_f32_e32 v83, v83
	v_exp_f32_e32 v84, v84
	v_exp_f32_e32 v85, v85
	v_exp_f32_e32 v86, v86
	v_exp_f32_e32 v87, v87
	v_exp_f32_e32 v112, v112
	v_exp_f32_e32 v113, v113
	v_exp_f32_e32 v114, v114
	v_exp_f32_e32 v115, v115
	v_exp_f32_e32 v116, v116
	v_exp_f32_e32 v117, v117
	v_exp_f32_e32 v118, v118
	v_exp_f32_e32 v119, v119
	v_pk_add_f32 v[244:245], v[244:245], v[80:81]
	v_pk_add_f32 v[246:247], v[246:247], v[112:113]
	v_pk_add_f32 v[244:245], v[244:245], v[82:83]
	v_pk_add_f32 v[246:247], v[246:247], v[114:115]
	v_pk_add_f32 v[244:245], v[244:245], v[84:85]
	v_pk_add_f32 v[246:247], v[246:247], v[116:117]
	v_pk_add_f32 v[244:245], v[244:245], v[86:87]
	v_pk_add_f32 v[246:247], v[246:247], v[118:119]
	v_cvt_pk_bf16_f32 v72, v80, v81
	v_cvt_pk_bf16_f32 v73, v82, v83
	v_cvt_pk_bf16_f32 v74, v84, v85
	v_cvt_pk_bf16_f32 v75, v86, v87
	v_cvt_pk_bf16_f32 v104, v112, v113
	v_cvt_pk_bf16_f32 v105, v114, v115
	v_cvt_pk_bf16_f32 v106, v116, v117
	v_cvt_pk_bf16_f32 v107, v118, v119
	s_waitcnt lgkmcnt(3)
	v_mfma_f32_32x32x16_bf16 v[0:15], v[192:195], v[72:75], v[0:15]
	v_mfma_f32_32x32x16_bf16 v[32:47], v[192:195], v[104:107], v[32:47]
	s_waitcnt lgkmcnt(2)
	v_mfma_f32_32x32x16_bf16 v[16:31], v[196:199], v[72:75], v[16:31]
	v_mfma_f32_32x32x16_bf16 v[48:63], v[196:199], v[104:107], v[48:63]
	v_exp_f32_e32 v88, v88
	v_exp_f32_e32 v89, v89
	v_exp_f32_e32 v90, v90
	v_exp_f32_e32 v91, v91
	v_exp_f32_e32 v92, v92
	v_exp_f32_e32 v93, v93
	v_exp_f32_e32 v94, v94
	v_exp_f32_e32 v95, v95
	v_exp_f32_e32 v120, v120
	v_exp_f32_e32 v121, v121
	v_exp_f32_e32 v122, v122
	v_exp_f32_e32 v123, v123
	v_exp_f32_e32 v124, v124
	v_exp_f32_e32 v125, v125
	v_exp_f32_e32 v126, v126
	v_exp_f32_e32 v127, v127
	v_pk_add_f32 v[244:245], v[244:245], v[88:89]
	v_pk_add_f32 v[246:247], v[246:247], v[120:121]
	v_pk_add_f32 v[244:245], v[244:245], v[90:91]
	v_pk_add_f32 v[246:247], v[246:247], v[122:123]
	v_pk_add_f32 v[244:245], v[244:245], v[92:93]
	v_pk_add_f32 v[246:247], v[246:247], v[124:125]
	v_pk_add_f32 v[244:245], v[244:245], v[94:95]
	v_pk_add_f32 v[246:247], v[246:247], v[126:127]
	v_cvt_pk_bf16_f32 v76, v88, v89
	v_cvt_pk_bf16_f32 v77, v90, v91
	v_cvt_pk_bf16_f32 v78, v92, v93
	v_cvt_pk_bf16_f32 v79, v94, v95
	v_cvt_pk_bf16_f32 v108, v120, v121
	v_cvt_pk_bf16_f32 v109, v122, v123
	v_cvt_pk_bf16_f32 v110, v124, v125
	v_cvt_pk_bf16_f32 v111, v126, v127
	s_waitcnt lgkmcnt(1)
	v_mfma_f32_32x32x16_bf16 v[0:15], v[200:203], v[76:79], v[0:15]
	v_mfma_f32_32x32x16_bf16 v[32:47], v[200:203], v[108:111], v[32:47]
	s_waitcnt lgkmcnt(0)
	v_mfma_f32_32x32x16_bf16 v[16:31], v[204:207], v[76:79], v[16:31]
	v_mfma_f32_32x32x16_bf16 v[48:63], v[204:207], v[108:111], v[48:63]
	s_add_u32 s68, s68, 1
	s_waitcnt lgkmcnt(0)
	s_barrier
	ds_read_b128 v[192:195], v128 offset:0
	ds_read_b128 v[196:199], v128 offset:4608
	ds_read_b128 v[200:203], v128 offset:32
	ds_read_b128 v[204:207], v128 offset:4640
	s_waitcnt lgkmcnt(3)
	v_mfma_f32_32x32x16_bf16 v[64:79], v[192:195], v[144:147], v[208:223]
	v_mfma_f32_32x32x16_bf16 v[96:111], v[192:195], v[168:171], v[208:223]
	ds_read_b128 v[192:195], v128 offset:64
	s_waitcnt lgkmcnt(3)
	v_mfma_f32_32x32x16_bf16 v[80:95], v[196:199], v[144:147], v[208:223]
	v_mfma_f32_32x32x16_bf16 v[112:127], v[196:199], v[168:171], v[208:223]
	ds_read_b128 v[196:199], v128 offset:4672
	s_waitcnt lgkmcnt(3)
	v_mfma_f32_32x32x16_bf16 v[64:79], v[200:203], v[148:151], v[64:79]
	v_mfma_f32_32x32x16_bf16 v[96:111], v[200:203], v[172:175], v[96:111]
	ds_read_b128 v[200:203], v128 offset:96
	s_waitcnt lgkmcnt(3)
	v_mfma_f32_32x32x16_bf16 v[80:95], v[204:207], v[148:151], v[80:95]
	v_mfma_f32_32x32x16_bf16 v[112:127], v[204:207], v[172:175], v[112:127]
	ds_read_b128 v[204:207], v128 offset:4704
	s_waitcnt lgkmcnt(3)
	v_mfma_f32_32x32x16_bf16 v[64:79], v[192:195], v[152:155], v[64:79]
	v_mfma_f32_32x32x16_bf16 v[96:111], v[192:195], v[176:179], v[96:111]
	s_waitcnt lgkmcnt(2)
	v_mfma_f32_32x32x16_bf16 v[80:95], v[196:199], v[152:155], v[80:95]
	v_mfma_f32_32x32x16_bf16 v[112:127], v[196:199], v[176:179], v[112:127]
	s_waitcnt lgkmcnt(1)
	v_mfma_f32_32x32x16_bf16 v[64:79], v[200:203], v[156:159], v[64:79]
	v_mfma_f32_32x32x16_bf16 v[96:111], v[200:203], v[180:183], v[96:111]
	s_waitcnt lgkmcnt(0)
	v_mfma_f32_32x32x16_bf16 v[80:95], v[204:207], v[156:159], v[80:95]
	v_mfma_f32_32x32x16_bf16 v[112:127], v[204:207], v[180:183], v[112:127]
	s_cmp_lt_u32 s68, 68
	s_cbranch_scc1 .Lat2_loop_g
; DI unsigned pack2(float lo, float hi) { f32x2_t v = {lo, hi}; bf16x2_t r = __builtin_convertvector(v, bf16x2_t); return __builtin_bit_cast(unsigned, r); }
; DI float xhalf_sum(float x) { auto r = __builtin_amdgcn_permlane32_swap(__float_as_uint(x), __float_as_uint(x), false, false); return __uint_as_float(r[0]) + __uint_as_float(r[1]); }
; template <int DQK>
; DI void attn_item(const bf16_t* __restrict__ Q, const bf16_t* __restrict__ Kp, const bf16_t* __restrict__ Vt, int q0, int nkeys,
;                   bf16_t* __restrict__ mix, int colbase, int b, char* smem) {
;     ...
;   l = xhalf_sum(l);
;   const float inv = 1.0f / l;
;   const int kp = q0 + wave * 32 + r;
;   bf16_t* orow = mix + (size_t)row_of(b, kp) * D + colbase;
; #pragma unroll
;   for (int g = 0; g < 4; ++g) {
;     uint2 w0, w1;
;     w0.x = pack2(o0[4 * g] * inv, o0[4 * g + 1] * inv); w0.y = pack2(o0[4 * g + 2] * inv, o0[4 * g + 3] * inv);
;     w1.x = pack2(o1[4 * g] * inv, o1[4 * g + 1] * inv); w1.y = pack2(o1[4 * g + 2] * inv, o1[4 * g + 3] * inv);
;     *(uint2*)(orow + 8 * g + 4 * h) = w0;
;     *(uint2*)(orow + 32 + 8 * g + 4 * h) = w1;
;   }
	s_waitcnt vmcnt(0)
	s_nop 7
	s_nop 7
	v_add_f32_e32 v244, v244, v245
	v_add_f32_e32 v246, v246, v247
	v_mov_b32_e32 v248, v244
	v_mov_b32_e32 v249, v246
	s_nop 1
	v_permlane32_swap_b32_e32 v244, v248
	v_permlane32_swap_b32_e32 v246, v249
	v_add_f32_e32 v244, v244, v248
	v_add_f32_e32 v246, v246, v249
	v_mov_b32_e32 v248, 0
	v_fmac_f32_e32 v248, 0, v0
	v_fmac_f32_e32 v248, 0, v1
	v_fmac_f32_e32 v248, 0, v2
	v_fmac_f32_e32 v248, 0, v3
	v_fmac_f32_e32 v248, 0, v4
	v_fmac_f32_e32 v248, 0, v5
	v_fmac_f32_e32 v248, 0, v6
	v_fmac_f32_e32 v248, 0, v7
	v_fmac_f32_e32 v248, 0, v8
	v_fmac_f32_e32 v248, 0, v9
	v_fmac_f32_e32 v248, 0, v10
	v_fmac_f32_e32 v248, 0, v11
	v_fmac_f32_e32 v248, 0, v12
	v_fmac_f32_e32 v248, 0, v13
	v_fmac_f32_e32 v248, 0, v14
	v_fmac_f32_e32 v248, 0, v15
	v_fmac_f32_e32 v248, 0, v16
	v_fmac_f32_e32 v248, 0, v17
	v_fmac_f32_e32 v248, 0, v18
	v_fmac_f32_e32 v248, 0, v19
	v_fmac_f32_e32 v248, 0, v20
	v_fmac_f32_e32 v248, 0, v21
	v_fmac_f32_e32 v248, 0, v22
	v_fmac_f32_e32 v248, 0, v23
	v_fmac_f32_e32 v248, 0, v24
	v_fmac_f32_e32 v248, 0, v25
	v_fmac_f32_e32 v248, 0, v26
	v_fmac_f32_e32 v248, 0, v27
	v_fmac_f32_e32 v248, 0, v28
	v_fmac_f32_e32 v248, 0, v29
	v_fmac_f32_e32 v248, 0, v30
	v_fmac_f32_e32 v248, 0, v31
	v_fmac_f32_e32 v248, 0, v32
	v_fmac_f32_e32 v248, 0, v33
	v_fmac_f32_e32 v248, 0, v34
	v_fmac_f32_e32 v248, 0, v35
	v_fmac_f32_e32 v248, 0, v36
	v_fmac_f32_e32 v248, 0, v37
	v_fmac_f32_e32 v248, 0, v38
	v_fmac_f32_e32 v248, 0, v39
	v_fmac_f32_e32 v248, 0, v40
	v_fmac_f32_e32 v248, 0, v41
	v_fmac_f32_e32 v248, 0, v42
	v_fmac_f32_e32 v248, 0, v43
	v_fmac_f32_e32 v248, 0, v44
	v_fmac_f32_e32 v248, 0, v45
	v_fmac_f32_e32 v248, 0, v46
	v_fmac_f32_e32 v248, 0, v47
	v_fmac_f32_e32 v248, 0, v48
	v_fmac_f32_e32 v248, 0, v49
	v_fmac_f32_e32 v248, 0, v50
	v_fmac_f32_e32 v248, 0, v51
	v_fmac_f32_e32 v248, 0, v52
	v_fmac_f32_e32 v248, 0, v53
	v_fmac_f32_e32 v248, 0, v54
	v_fmac_f32_e32 v248, 0, v55
	v_fmac_f32_e32 v248, 0, v56
	v_fmac_f32_e32 v248, 0, v57
	v_fmac_f32_e32 v248, 0, v58
	v_fmac_f32_e32 v248, 0, v59
	v_fmac_f32_e32 v248, 0, v60
	v_fmac_f32_e32 v248, 0, v61
	v_fmac_f32_e32 v248, 0, v62
	v_fmac_f32_e32 v248, 0, v63
	v_mov_b32_e32 v249, 0x71800000
	v_mov_b32_e32 v250, 0x21800000
	v_cmp_neq_f32_e32 vcc, 0, v248
	s_mov_b64 s[44:45], vcc
	v_cmp_nlt_f32_e32 vcc, v244, v249
	s_or_b64 s[44:45], vcc, s[44:45]
	v_cmp_ngt_f32_e32 vcc, v244, v250
	s_or_b64 s[44:45], vcc, s[44:45]
	v_cmp_nlt_f32_e32 vcc, v246, v249
	s_or_b64 s[44:45], vcc, s[44:45]
	v_cmp_ngt_f32_e32 vcc, v246, v250
	s_or_b64 s[44:45], vcc, s[44:45]
	s_cmp_lg_u64 s[44:45], 0
	s_cselect_b32 s0, 1, 0
	v_mov_b32_e32 v250, s0
	s_lshl_b32 s1, s57, 2
	s_add_u32 s1, s1, 0x13400
	v_mov_b32_e32 v251, s1
	v_mov_b32_e32 v252, 0x13400
	ds_write_b32 v251, v250
	s_waitcnt lgkmcnt(0)
	s_barrier
	ds_read_b128 v[192:195], v252
	s_waitcnt lgkmcnt(0)
	v_or3_b32 v250, v192, v193, v194
	v_or_b32_e32 v250, v250, v195
	s_nop 0
	v_readfirstlane_b32 s0, v250
	s_nop 3
	s_cmp_eq_u32 s0, 0
	s_cbranch_scc0 .Lat2_fallback
	v_rcp_f32_e32 v248, v244
	v_rcp_f32_e32 v249, v246
	s_nop 0
	v_mul_f32_e32 v64, v0, v248
	v_mul_f32_e32 v65, v1, v248
	v_mul_f32_e32 v66, v2, v248
	v_mul_f32_e32 v67, v3, v248
	v_cvt_pk_bf16_f32 v192, v64, v65
	v_cvt_pk_bf16_f32 v193, v66, v67
	global_store_dwordx2 v141, v[192:193], s[72:73] offset:0
	v_mul_f32_e32 v64, v16, v248
	v_mul_f32_e32 v65, v17, v248
	v_mul_f32_e32 v66, v18, v248
	v_mul_f32_e32 v67, v19, v248
	v_cvt_pk_bf16_f32 v194, v64, v65
	v_cvt_pk_bf16_f32 v195, v66, v67
	global_store_dwordx2 v142, v[194:195], s[72:73] offset:0
	v_mul_f32_e32 v64, v4, v248
	v_mul_f32_e32 v65, v5, v248
	v_mul_f32_e32 v66, v6, v248
	v_mul_f32_e32 v67, v7, v248
	v_cvt_pk_bf16_f32 v196, v64, v65
	v_cvt_pk_bf16_f32 v197, v66, v67
	global_store_dwordx2 v141, v[196:197], s[72:73] offset:16
	v_mul_f32_e32 v64, v20, v248
	v_mul_f32_e32 v65, v21, v248
	v_mul_f32_e32 v66, v22, v248
	v_mul_f32_e32 v67, v23, v248
	v_cvt_pk_bf16_f32 v198, v64, v65
	v_cvt_pk_bf16_f32 v199, v66, v67
	global_store_dwordx2 v142, v[198:199], s[72:73] offset:16
	v_mul_f32_e32 v64, v8, v248
	v_mul_f32_e32 v65, v9, v248
	v_mul_f32_e32 v66, v10, v248
	v_mul_f32_e32 v67, v11, v248
	v_cvt_pk_bf16_f32 v200, v64, v65
	v_cvt_pk_bf16_f32 v201, v66, v67
	global_store_dwordx2 v141, v[200:201], s[72:73] offset:32
	v_mul_f32_e32 v64, v24, v248
	v_mul_f32_e32 v65, v25, v248
	v_mul_f32_e32 v66, v26, v248
	v_mul_f32_e32 v67, v27, v248
	v_cvt_pk_bf16_f32 v202, v64, v65
	v_cvt_pk_bf16_f32 v203, v66, v67
	global_store_dwordx2 v142, v[202:203], s[72:73] offset:32
	v_mul_f32_e32 v64, v12, v248
	v_mul_f32_e32 v65, v13, v248
	v_mul_f32_e32 v66, v14, v248
	v_mul_f32_e32 v67, v15, v248
	v_cvt_pk_bf16_f32 v204, v64, v65
	v_cvt_pk_bf16_f32 v205, v66, v67
	global_store_dwordx2 v141, v[204:205], s[72:73] offset:48
	v_mul_f32_e32 v64, v28, v248
	v_mul_f32_e32 v65, v29, v248
	v_mul_f32_e32 v66, v30, v248
	v_mul_f32_e32 v67, v31, v248
	v_cvt_pk_bf16_f32 v206, v64, v65
	v_cvt_pk_bf16_f32 v207, v66, v67
	global_store_dwordx2 v142, v[206:207], s[72:73] offset:48
	v_mul_f32_e32 v64, v32, v249
	v_mul_f32_e32 v65, v33, v249
	v_mul_f32_e32 v66, v34, v249
	v_mul_f32_e32 v67, v35, v249
	v_cvt_pk_bf16_f32 v192, v64, v65
	v_cvt_pk_bf16_f32 v193, v66, v67
	global_store_dwordx2 v141, v[192:193], s[76:77] offset:0
	v_mul_f32_e32 v64, v48, v249
	v_mul_f32_e32 v65, v49, v249
	v_mul_f32_e32 v66, v50, v249
	v_mul_f32_e32 v67, v51, v249
	v_cvt_pk_bf16_f32 v194, v64, v65
	v_cvt_pk_bf16_f32 v195, v66, v67
	global_store_dwordx2 v142, v[194:195], s[76:77] offset:0
	v_mul_f32_e32 v64, v36, v249
	v_mul_f32_e32 v65, v37, v249
	v_mul_f32_e32 v66, v38, v249
	v_mul_f32_e32 v67, v39, v249
	v_cvt_pk_bf16_f32 v196, v64, v65
	v_cvt_pk_bf16_f32 v197, v66, v67
	global_store_dwordx2 v141, v[196:197], s[76:77] offset:16
	v_mul_f32_e32 v64, v52, v249
	v_mul_f32_e32 v65, v53, v249
	v_mul_f32_e32 v66, v54, v249
	v_mul_f32_e32 v67, v55, v249
	v_cvt_pk_bf16_f32 v198, v64, v65
	v_cvt_pk_bf16_f32 v199, v66, v67
	global_store_dwordx2 v142, v[198:199], s[76:77] offset:16
	v_mul_f32_e32 v64, v40, v249
	v_mul_f32_e32 v65, v41, v249
	v_mul_f32_e32 v66, v42, v249
	v_mul_f32_e32 v67, v43, v249
	v_cvt_pk_bf16_f32 v200, v64, v65
	v_cvt_pk_bf16_f32 v201, v66, v67
	global_store_dwordx2 v141, v[200:201], s[76:77] offset:32
	v_mul_f32_e32 v64, v56, v249
	v_mul_f32_e32 v65, v57, v249
	v_mul_f32_e32 v66, v58, v249
	v_mul_f32_e32 v67, v59, v249
	v_cvt_pk_bf16_f32 v202, v64, v65
	v_cvt_pk_bf16_f32 v203, v66, v67
	global_store_dwordx2 v142, v[202:203], s[76:77] offset:32
	v_mul_f32_e32 v64, v44, v249
	v_mul_f32_e32 v65, v45, v249
	v_mul_f32_e32 v66, v46, v249
	v_mul_f32_e32 v67, v47, v249
	v_cvt_pk_bf16_f32 v204, v64, v65
	v_cvt_pk_bf16_f32 v205, v66, v67
	global_store_dwordx2 v141, v[204:205], s[76:77] offset:48
	v_mul_f32_e32 v64, v60, v249
	v_mul_f32_e32 v65, v61, v249
	v_mul_f32_e32 v66, v62, v249
	v_mul_f32_e32 v67, v63, v249
	v_cvt_pk_bf16_f32 v206, v64, v65
	v_cvt_pk_bf16_f32 v207, v66, v67
	global_store_dwordx2 v142, v[206:207], s[76:77] offset:48
	s_branch .Lat2_next

; template <int DQK>
; DI void attn_item(const bf16_t* __restrict__ Q, const bf16_t* __restrict__ Kp, const bf16_t* __restrict__ Vt, int q0, int nkeys,
;                   bf16_t* __restrict__ mix, int colbase, int b, char* smem) {
;     ...
;   const int nt = nkeys >> 6;
;   A_LOAD(p, 0)
;   A_LOAD(q, 64)
;   A_WRITE(p, 0)
;   __syncthreads();
;   if (nt > 2) A_LOAD(p, 128)
;   for (int kt = 0; kt < nt; kt += 2) {
;     A_TILE(0)
;     A_WRITE(q, 1)
;     __syncthreads();
;     if (kt + 3 < nt) A_LOAD(q, (kt + 3) << 6)
;     A_TILE(1)
;     if (kt + 2 < nt) A_WRITE(p, 0)
;     __syncthreads();
;     if (kt + 4 < nt) A_LOAD(p, (kt + 4) << 6)
;   }
.Lat2_loop_m:
	s_waitcnt vmcnt(0)
	ds_write_b128 v131, v[224:227] offset:13312
	ds_write_b128 v132, v[228:231] offset:13312
	ds_write_b128 v133, v[232:235] offset:13312
	ds_write_b64 v134, v[236:237] offset:35328
	ds_write_b64 v134, v[238:239] offset:35336
	ds_write_b64 v135, v[240:241] offset:35328
	ds_write_b64 v135, v[242:243] offset:35336
	s_add_u32 s1, s68, 2
	s_min_u32 s0, s1, 67
	s_mul_i32 s10, s0, 0x3000
	s_add_u32 s64, s60, s10
	s_addc_u32 s65, s61, 0
	s_lshl_b32 s0, s0, 7
	s_add_u32 s66, s62, s0
	s_addc_u32 s67, s63, 0
	global_load_dwordx4 v[224:227], v136, s[64:65]
	global_load_dwordx4 v[228:231], v137, s[64:65]
	global_load_dwordx4 v[232:235], v138, s[64:65]
	global_load_dwordx4 v[236:239], v139, s[66:67]
	global_load_dwordx4 v[240:243], v140, s[66:67]
	v_add_u32_e32 v248, 0x6800, v129
	v_add_u32_e32 v249, 0x6800, v130
	ds_read2_b64 v[192:195], v248 offset0:0 offset1:2
	ds_read2_b64 v[196:199], v249 offset0:0 offset1:2
	ds_read2_b64 v[200:203], v248 offset0:4 offset1:6
	ds_read2_b64 v[204:207], v249 offset0:4 offset1:6
	v_exp_f32_e32 v64, v64
	v_exp_f32_e32 v65, v65
	v_exp_f32_e32 v66, v66
	v_exp_f32_e32 v67, v67
	v_exp_f32_e32 v68, v68
	v_exp_f32_e32 v69, v69
	v_exp_f32_e32 v70, v70
	v_exp_f32_e32 v71, v71
	v_exp_f32_e32 v96, v96
	v_exp_f32_e32 v97, v97
	v_exp_f32_e32 v98, v98
	v_exp_f32_e32 v99, v99
	v_exp_f32_e32 v100, v100
	v_exp_f32_e32 v101, v101
	v_exp_f32_e32 v102, v102
	v_exp_f32_e32 v103, v103
	v_pk_add_f32 v[244:245], v[244:245], v[64:65]
	v_pk_add_f32 v[246:247], v[246:247], v[96:97]
	v_pk_add_f32 v[244:245], v[244:245], v[66:67]
	v_pk_add_f32 v[246:247], v[246:247], v[98:99]
	v_pk_add_f32 v[244:245], v[244:245], v[68:69]
	v_pk_add_f32 v[246:247], v[246:247], v[100:101]
	v_pk_add_f32 v[244:245], v[244:245], v[70:71]
	v_pk_add_f32 v[246:247], v[246:247], v[102:103]
	v_cvt_pk_bf16_f32 v64, v64, v65
	v_cvt_pk_bf16_f32 v65, v66, v67
	v_cvt_pk_bf16_f32 v66, v68, v69
	v_cvt_pk_bf16_f32 v67, v70, v71
	v_cvt_pk_bf16_f32 v96, v96, v97
	v_cvt_pk_bf16_f32 v97, v98, v99
	v_cvt_pk_bf16_f32 v98, v100, v101
	v_cvt_pk_bf16_f32 v99, v102, v103
	s_waitcnt lgkmcnt(3)
	v_mfma_f32_32x32x16_bf16 v[0:15], v[192:195], v[64:67], v[0:15]
	v_mfma_f32_32x32x16_bf16 v[32:47], v[192:195], v[96:99], v[32:47]
	ds_read2_b64 v[192:195], v248 offset0:8 offset1:10
	s_waitcnt lgkmcnt(3)
	v_mfma_f32_32x32x16_bf16 v[16:31], v[196:199], v[64:67], v[16:31]
	v_mfma_f32_32x32x16_bf16 v[48:63], v[196:199], v[96:99], v[48:63]
	ds_read2_b64 v[196:199], v249 offset0:8 offset1:10
	v_exp_f32_e32 v72, v72
	v_exp_f32_e32 v73, v73
	v_exp_f32_e32 v74, v74
	v_exp_f32_e32 v75, v75
	v_exp_f32_e32 v76, v76
	v_exp_f32_e32 v77, v77
	v_exp_f32_e32 v78, v78
	v_exp_f32_e32 v79, v79
	v_exp_f32_e32 v104, v104
	v_exp_f32_e32 v105, v105
	v_exp_f32_e32 v106, v106
	v_exp_f32_e32 v107, v107
	v_exp_f32_e32 v108, v108
	v_exp_f32_e32 v109, v109
	v_exp_f32_e32 v110, v110
	v_exp_f32_e32 v111, v111
	v_pk_add_f32 v[244:245], v[244:245], v[72:73]
	v_pk_add_f32 v[246:247], v[246:247], v[104:105]
	v_pk_add_f32 v[244:245], v[244:245], v[74:75]
	v_pk_add_f32 v[246:247], v[246:247], v[106:107]
	v_pk_add_f32 v[244:245], v[244:245], v[76:77]
	v_pk_add_f32 v[246:247], v[246:247], v[108:109]
	v_pk_add_f32 v[244:245], v[244:245], v[78:79]
	v_pk_add_f32 v[246:247], v[246:247], v[110:111]
	v_cvt_pk_bf16_f32 v68, v72, v73
	v_cvt_pk_bf16_f32 v69, v74, v75
	v_cvt_pk_bf16_f32 v70, v76, v77
	v_cvt_pk_bf16_f32 v71, v78, v79
	v_cvt_pk_bf16_f32 v100, v104, v105
	v_cvt_pk_bf16_f32 v101, v106, v107
	v_cvt_pk_bf16_f32 v102, v108, v109
	v_cvt_pk_bf16_f32 v103, v110, v111
	s_waitcnt lgkmcnt(3)
	v_mfma_f32_32x32x16_bf16 v[0:15], v[200:203], v[68:71], v[0:15]
	v_mfma_f32_32x32x16_bf16 v[32:47], v[200:203], v[100:103], v[32:47]
	ds_read2_b64 v[200:203], v248 offset0:12 offset1:14
	s_waitcnt lgkmcnt(3)
	v_mfma_f32_32x32x16_bf16 v[16:31], v[204:207], v[68:71], v[16:31]
	v_mfma_f32_32x32x16_bf16 v[48:63], v[204:207], v[100:103], v[48:63]
	ds_read2_b64 v[204:207], v249 offset0:12 offset1:14
	v_exp_f32_e32 v80, v80
	v_exp_f32_e32 v81, v81
	v_exp_f32_e32 v82, v82
	v_exp_f32_e32 v83, v83
	v_exp_f32_e32 v84, v84
	v_exp_f32_e32 v85, v85
	v_exp_f32_e32 v86, v86
	v_exp_f32_e32 v87, v87
	v_exp_f32_e32 v112, v112
	v_exp_f32_e32 v113, v113
	v_exp_f32_e32 v114, v114
	v_exp_f32_e32 v115, v115
	v_exp_f32_e32 v116, v116
	v_exp_f32_e32 v117, v117
	v_exp_f32_e32 v118, v118
	v_exp_f32_e32 v119, v119
	v_pk_add_f32 v[244:245], v[244:245], v[80:81]
	v_pk_add_f32 v[246:247], v[246:247], v[112:113]
	v_pk_add_f32 v[244:245], v[244:245], v[82:83]
	v_pk_add_f32 v[246:247], v[246:247], v[114:115]
	v_pk_add_f32 v[244:245], v[244:245], v[84:85]
	v_pk_add_f32 v[246:247], v[246:247], v[116:117]
	v_pk_add_f32 v[244:245], v[244:245], v[86:87]
	v_pk_add_f32 v[246:247], v[246:247], v[118:119]
	v_cvt_pk_bf16_f32 v72, v80, v81
	v_cvt_pk_bf16_f32 v73, v82, v83
	v_cvt_pk_bf16_f32 v74, v84, v85
	v_cvt_pk_bf16_f32 v75, v86, v87
	v_cvt_pk_bf16_f32 v104, v112, v113
	v_cvt_pk_bf16_f32 v105, v114, v115
	v_cvt_pk_bf16_f32 v106, v116, v117
	v_cvt_pk_bf16_f32 v107, v118, v119
	s_waitcnt lgkmcnt(3)
	v_mfma_f32_32x32x16_bf16 v[0:15], v[192:195], v[72:75], v[0:15]
	v_mfma_f32_32x32x16_bf16 v[32:47], v[192:195], v[104:107], v[32:47]
	s_waitcnt lgkmcnt(2)
	v_mfma_f32_32x32x16_bf16 v[16:31], v[196:199], v[72:75], v[16:31]
	v_mfma_f32_32x32x16_bf16 v[48:63], v[196:199], v[104:107], v[48:63]
	v_exp_f32_e32 v88, v88
	v_exp_f32_e32 v89, v89
	v_exp_f32_e32 v90, v90
	v_exp_f32_e32 v91, v91
	v_exp_f32_e32 v92, v92
	v_exp_f32_e32 v93, v93
	v_exp_f32_e32 v94, v94
	v_exp_f32_e32 v95, v95
	v_exp_f32_e32 v120, v120
	v_exp_f32_e32 v121, v121
	v_exp_f32_e32 v122, v122
	v_exp_f32_e32 v123, v123
	v_exp_f32_e32 v124, v124
	v_exp_f32_e32 v125, v125
	v_exp_f32_e32 v126, v126
	v_exp_f32_e32 v127, v127
	v_pk_add_f32 v[244:245], v[244:245], v[88:89]
	v_pk_add_f32 v[246:247], v[246:247], v[120:121]
	v_pk_add_f32 v[244:245], v[244:245], v[90:91]
	v_pk_add_f32 v[246:247], v[246:247], v[122:123]
	v_pk_add_f32 v[244:245], v[244:245], v[92:93]
	v_pk_add_f32 v[246:247], v[246:247], v[124:125]
	v_pk_add_f32 v[244:245], v[244:245], v[94:95]
	v_pk_add_f32 v[246:247], v[246:247], v[126:127]
	v_cvt_pk_bf16_f32 v76, v88, v89
	v_cvt_pk_bf16_f32 v77, v90, v91
	v_cvt_pk_bf16_f32 v78, v92, v93
	v_cvt_pk_bf16_f32 v79, v94, v95
	v_cvt_pk_bf16_f32 v108, v120, v121
	v_cvt_pk_bf16_f32 v109, v122, v123
	v_cvt_pk_bf16_f32 v110, v124, v125
	v_cvt_pk_bf16_f32 v111, v126, v127
	s_waitcnt lgkmcnt(1)
	v_mfma_f32_32x32x16_bf16 v[0:15], v[200:203], v[76:79], v[0:15]
	v_mfma_f32_32x32x16_bf16 v[32:47], v[200:203], v[108:111], v[32:47]
	s_waitcnt lgkmcnt(0)
	v_mfma_f32_32x32x16_bf16 v[16:31], v[204:207], v[76:79], v[16:31]
	v_mfma_f32_32x32x16_bf16 v[48:63], v[204:207], v[108:111], v[48:63]
	s_add_u32 s68, s68, 1
	s_waitcnt lgkmcnt(0)
	s_barrier
; template <int DQK>
; DI void attn_item(const bf16_t* __restrict__ Q, const bf16_t* __restrict__ Kp, const bf16_t* __restrict__ Vt, int q0, int nkeys,
;                   bf16_t* __restrict__ mix, int colbase, int b, char* smem) {
;     ...
;   const int nt = nkeys >> 6;
;   A_LOAD(p, 0)
;   A_LOAD(q, 64)
;   A_WRITE(p, 0)
;   __syncthreads();
;   if (nt > 2) A_LOAD(p, 128)
;   for (int kt = 0; kt < nt; kt += 2) {
;     A_TILE(0)
;     A_WRITE(q, 1)
;     __syncthreads();
;     if (kt + 3 < nt) A_LOAD(q, (kt + 3) << 6)
;     A_TILE(1)
;     if (kt + 2 < nt) A_WRITE(p, 0)
;     __syncthreads();
;     if (kt + 4 < nt) A_LOAD(p, (kt + 4) << 6)
	ds_read_b128 v[192:195], v128 offset:13312
	ds_read_b128 v[196:199], v128 offset:19968
	ds_read_b128 v[200:203], v128 offset:13344
	ds_read_b128 v[204:207], v128 offset:20000
	s_waitcnt lgkmcnt(3)
	v_mfma_f32_32x32x16_bf16 v[64:79], v[192:195], v[144:147], v[208:223]
	v_mfma_f32_32x32x16_bf16 v[96:111], v[192:195], v[168:171], v[208:223]
	ds_read_b128 v[192:195], v128 offset:13376
	s_waitcnt lgkmcnt(3)
	v_mfma_f32_32x32x16_bf16 v[80:95], v[196:199], v[144:147], v[208:223]
	v_mfma_f32_32x32x16_bf16 v[112:127], v[196:199], v[168:171], v[208:223]
	ds_read_b128 v[196:199], v128 offset:20032
	s_waitcnt lgkmcnt(3)
	v_mfma_f32_32x32x16_bf16 v[64:79], v[200:203], v[148:151], v[64:79]
	v_mfma_f32_32x32x16_bf16 v[96:111], v[200:203], v[172:175], v[96:111]
	ds_read_b128 v[200:203], v128 offset:13408
	s_waitcnt lgkmcnt(3)
	v_mfma_f32_32x32x16_bf16 v[80:95], v[204:207], v[148:151], v[80:95]
	v_mfma_f32_32x32x16_bf16 v[112:127], v[204:207], v[172:175], v[112:127]
	ds_read_b128 v[204:207], v128 offset:20064
	s_waitcnt lgkmcnt(3)
	v_mfma_f32_32x32x16_bf16 v[64:79], v[192:195], v[152:155], v[64:79]
	v_mfma_f32_32x32x16_bf16 v[96:111], v[192:195], v[176:179], v[96:111]
	ds_read_b128 v[192:195], v128 offset:13440
	s_waitcnt lgkmcnt(3)
	v_mfma_f32_32x32x16_bf16 v[80:95], v[196:199], v[152:155], v[80:95]
	v_mfma_f32_32x32x16_bf16 v[112:127], v[196:199], v[176:179], v[112:127]
	ds_read_b128 v[196:199], v128 offset:20096
	s_waitcnt lgkmcnt(3)
	v_mfma_f32_32x32x16_bf16 v[64:79], v[200:203], v[156:159], v[64:79]
	v_mfma_f32_32x32x16_bf16 v[96:111], v[200:203], v[180:183], v[96:111]
	ds_read_b128 v[200:203], v128 offset:13472
	s_waitcnt lgkmcnt(3)
	v_mfma_f32_32x32x16_bf16 v[80:95], v[204:207], v[156:159], v[80:95]
	v_mfma_f32_32x32x16_bf16 v[112:127], v[204:207], v[180:183], v[112:127]
	ds_read_b128 v[204:207], v128 offset:20128
	s_waitcnt lgkmcnt(3)
	v_mfma_f32_32x32x16_bf16 v[64:79], v[192:195], v[160:163], v[64:79]
	v_mfma_f32_32x32x16_bf16 v[96:111], v[192:195], v[184:187], v[96:111]
	s_waitcnt lgkmcnt(2)
	v_mfma_f32_32x32x16_bf16 v[80:95], v[196:199], v[160:163], v[80:95]
	v_mfma_f32_32x32x16_bf16 v[112:127], v[196:199], v[184:187], v[112:127]
	s_waitcnt lgkmcnt(1)
	v_mfma_f32_32x32x16_bf16 v[64:79], v[200:203], v[164:167], v[64:79]
	v_mfma_f32_32x32x16_bf16 v[96:111], v[200:203], v[188:191], v[96:111]
	s_waitcnt lgkmcnt(0)
	v_mfma_f32_32x32x16_bf16 v[80:95], v[204:207], v[164:167], v[80:95]
	v_mfma_f32_32x32x16_bf16 v[112:127], v[204:207], v[188:191], v[112:127]
	s_waitcnt vmcnt(0)
	ds_write_b128 v131, v[224:227] offset:0
	ds_write_b128 v132, v[228:231] offset:0
	ds_write_b128 v133, v[232:235] offset:0
	ds_write_b64 v134, v[236:237] offset:26624
	ds_write_b64 v134, v[238:239] offset:26632
	ds_write_b64 v135, v[240:241] offset:26624
	ds_write_b64 v135, v[242:243] offset:26632
	s_add_u32 s1, s68, 2
	s_min_u32 s0, s1, 67
	s_mul_i32 s10, s0, 0x3000
	s_add_u32 s64, s60, s10
	s_addc_u32 s65, s61, 0
	s_lshl_b32 s0, s0, 7
	s_add_u32 s66, s62, s0
	s_addc_u32 s67, s63, 0
	global_load_dwordx4 v[224:227], v136, s[64:65]
	global_load_dwordx4 v[228:231], v137, s[64:65]
	global_load_dwordx4 v[232:235], v138, s[64:65]
	global_load_dwordx4 v[236:239], v139, s[66:67]
	global_load_dwordx4 v[240:243], v140, s[66:67]
	v_add_u32_e32 v248, 0x8a00, v129
	v_add_u32_e32 v249, 0x8a00, v130
	ds_read2_b64 v[192:195], v248 offset0:0 offset1:2
	ds_read2_b64 v[196:199], v249 offset0:0 offset1:2
	ds_read2_b64 v[200:203], v248 offset0:4 offset1:6
	ds_read2_b64 v[204:207], v249 offset0:4 offset1:6
	v_exp_f32_e32 v64, v64
	v_exp_f32_e32 v65, v65
	v_exp_f32_e32 v66, v66
	v_exp_f32_e32 v67, v67
	v_exp_f32_e32 v68, v68
	v_exp_f32_e32 v69, v69
	v_exp_f32_e32 v70, v70
	v_exp_f32_e32 v71, v71
	v_exp_f32_e32 v96, v96
	v_exp_f32_e32 v97, v97
	v_exp_f32_e32 v98, v98
	v_exp_f32_e32 v99, v99
	v_exp_f32_e32 v100, v100
	v_exp_f32_e32 v101, v101
	v_exp_f32_e32 v102, v102
	v_exp_f32_e32 v103, v103
	v_pk_add_f32 v[244:245], v[244:245], v[64:65]
	v_pk_add_f32 v[246:247], v[246:247], v[96:97]
	v_pk_add_f32 v[244:245], v[244:245], v[66:67]
	v_pk_add_f32 v[246:247], v[246:247], v[98:99]
	v_pk_add_f32 v[244:245], v[244:245], v[68:69]
	v_pk_add_f32 v[246:247], v[246:247], v[100:101]
	v_pk_add_f32 v[244:245], v[244:245], v[70:71]
	v_pk_add_f32 v[246:247], v[246:247], v[102:103]
	v_cvt_pk_bf16_f32 v64, v64, v65
	v_cvt_pk_bf16_f32 v65, v66, v67
	v_cvt_pk_bf16_f32 v66, v68, v69
	v_cvt_pk_bf16_f32 v67, v70, v71
	v_cvt_pk_bf16_f32 v96, v96, v97
	v_cvt_pk_bf16_f32 v97, v98, v99
	v_cvt_pk_bf16_f32 v98, v100, v101
	v_cvt_pk_bf16_f32 v99, v102, v103
	s_waitcnt lgkmcnt(3)
	v_mfma_f32_32x32x16_bf16 v[0:15], v[192:195], v[64:67], v[0:15]
	v_mfma_f32_32x32x16_bf16 v[32:47], v[192:195], v[96:99], v[32:47]
	ds_read2_b64 v[192:195], v248 offset0:8 offset1:10
	s_waitcnt lgkmcnt(3)
	v_mfma_f32_32x32x16_bf16 v[16:31], v[196:199], v[64:67], v[16:31]
	v_mfma_f32_32x32x16_bf16 v[48:63], v[196:199], v[96:99], v[48:63]
	ds_read2_b64 v[196:199], v249 offset0:8 offset1:10
	v_exp_f32_e32 v72, v72
	v_exp_f32_e32 v73, v73
	v_exp_f32_e32 v74, v74
	v_exp_f32_e32 v75, v75
	v_exp_f32_e32 v76, v76
	v_exp_f32_e32 v77, v77
	v_exp_f32_e32 v78, v78
	v_exp_f32_e32 v79, v79
	v_exp_f32_e32 v104, v104
	v_exp_f32_e32 v105, v105
	v_exp_f32_e32 v106, v106
	v_exp_f32_e32 v107, v107
	v_exp_f32_e32 v108, v108
	v_exp_f32_e32 v109, v109
	v_exp_f32_e32 v110, v110
	v_exp_f32_e32 v111, v111
	v_pk_add_f32 v[244:245], v[244:245], v[72:73]
	v_pk_add_f32 v[246:247], v[246:247], v[104:105]
	v_pk_add_f32 v[244:245], v[244:245], v[74:75]
	v_pk_add_f32 v[246:247], v[246:247], v[106:107]
	v_pk_add_f32 v[244:245], v[244:245], v[76:77]
	v_pk_add_f32 v[246:247], v[246:247], v[108:109]
	v_pk_add_f32 v[244:245], v[244:245], v[78:79]
	v_pk_add_f32 v[246:247], v[246:247], v[110:111]
	v_cvt_pk_bf16_f32 v68, v72, v73
	v_cvt_pk_bf16_f32 v69, v74, v75
	v_cvt_pk_bf16_f32 v70, v76, v77
	v_cvt_pk_bf16_f32 v71, v78, v79
	v_cvt_pk_bf16_f32 v100, v104, v105
	v_cvt_pk_bf16_f32 v101, v106, v107
	v_cvt_pk_bf16_f32 v102, v108, v109
	v_cvt_pk_bf16_f32 v103, v110, v111
	s_waitcnt lgkmcnt(3)
; template <int DQK>
; DI void attn_item(const bf16_t* __restrict__ Q, const bf16_t* __restrict__ Kp, const bf16_t* __restrict__ Vt, int q0, int nkeys,
;                   bf16_t* __restrict__ mix, int colbase, int b, char* smem) {
;     ...
;   const int nt = nkeys >> 6;
;   A_LOAD(p, 0)
;   A_LOAD(q, 64)
;   A_WRITE(p, 0)
;   __syncthreads();
;   if (nt > 2) A_LOAD(p, 128)
;   for (int kt = 0; kt < nt; kt += 2) {
;     A_TILE(0)
;     A_WRITE(q, 1)
;     __syncthreads();
;     if (kt + 3 < nt) A_LOAD(q, (kt + 3) << 6)
;     A_TILE(1)
;     if (kt + 2 < nt) A_WRITE(p, 0)
;     __syncthreads();
;     if (kt + 4 < nt) A_LOAD(p, (kt + 4) << 6)
	v_mfma_f32_32x32x16_bf16 v[0:15], v[200:203], v[68:71], v[0:15]
	v_mfma_f32_32x32x16_bf16 v[32:47], v[200:203], v[100:103], v[32:47]
	ds_read2_b64 v[200:203], v248 offset0:12 offset1:14
	s_waitcnt lgkmcnt(3)
	v_mfma_f32_32x32x16_bf16 v[16:31], v[204:207], v[68:71], v[16:31]
	v_mfma_f32_32x32x16_bf16 v[48:63], v[204:207], v[100:103], v[48:63]
	ds_read2_b64 v[204:207], v249 offset0:12 offset1:14
	v_exp_f32_e32 v80, v80
	v_exp_f32_e32 v81, v81
	v_exp_f32_e32 v82, v82
	v_exp_f32_e32 v83, v83
	v_exp_f32_e32 v84, v84
	v_exp_f32_e32 v85, v85
	v_exp_f32_e32 v86, v86
	v_exp_f32_e32 v87, v87
	v_exp_f32_e32 v112, v112
	v_exp_f32_e32 v113, v113
	v_exp_f32_e32 v114, v114
	v_exp_f32_e32 v115, v115
	v_exp_f32_e32 v116, v116
	v_exp_f32_e32 v117, v117
	v_exp_f32_e32 v118, v118
	v_exp_f32_e32 v119, v119
	v_pk_add_f32 v[244:245], v[244:245], v[80:81]
	v_pk_add_f32 v[246:247], v[246:247], v[112:113]
	v_pk_add_f32 v[244:245], v[244:245], v[82:83]
	v_pk_add_f32 v[246:247], v[246:247], v[114:115]
	v_pk_add_f32 v[244:245], v[244:245], v[84:85]
	v_pk_add_f32 v[246:247], v[246:247], v[116:117]
	v_pk_add_f32 v[244:245], v[244:245], v[86:87]
	v_pk_add_f32 v[246:247], v[246:247], v[118:119]
	v_cvt_pk_bf16_f32 v72, v80, v81
	v_cvt_pk_bf16_f32 v73, v82, v83
	v_cvt_pk_bf16_f32 v74, v84, v85
	v_cvt_pk_bf16_f32 v75, v86, v87
	v_cvt_pk_bf16_f32 v104, v112, v113
	v_cvt_pk_bf16_f32 v105, v114, v115
	v_cvt_pk_bf16_f32 v106, v116, v117
	v_cvt_pk_bf16_f32 v107, v118, v119
	s_waitcnt lgkmcnt(3)
	v_mfma_f32_32x32x16_bf16 v[0:15], v[192:195], v[72:75], v[0:15]
	v_mfma_f32_32x32x16_bf16 v[32:47], v[192:195], v[104:107], v[32:47]
	s_waitcnt lgkmcnt(2)
	v_mfma_f32_32x32x16_bf16 v[16:31], v[196:199], v[72:75], v[16:31]
	v_mfma_f32_32x32x16_bf16 v[48:63], v[196:199], v[104:107], v[48:63]
	v_exp_f32_e32 v88, v88
	v_exp_f32_e32 v89, v89
	v_exp_f32_e32 v90, v90
	v_exp_f32_e32 v91, v91
	v_exp_f32_e32 v92, v92
	v_exp_f32_e32 v93, v93
	v_exp_f32_e32 v94, v94
	v_exp_f32_e32 v95, v95
	v_exp_f32_e32 v120, v120
	v_exp_f32_e32 v121, v121
	v_exp_f32_e32 v122, v122
	v_exp_f32_e32 v123, v123
	v_exp_f32_e32 v124, v124
	v_exp_f32_e32 v125, v125
	v_exp_f32_e32 v126, v126
	v_exp_f32_e32 v127, v127
	v_pk_add_f32 v[244:245], v[244:245], v[88:89]
	v_pk_add_f32 v[246:247], v[246:247], v[120:121]
	v_pk_add_f32 v[244:245], v[244:245], v[90:91]
	v_pk_add_f32 v[246:247], v[246:247], v[122:123]
	v_pk_add_f32 v[244:245], v[244:245], v[92:93]
	v_pk_add_f32 v[246:247], v[246:247], v[124:125]
	v_pk_add_f32 v[244:245], v[244:245], v[94:95]
	v_pk_add_f32 v[246:247], v[246:247], v[126:127]
	v_cvt_pk_bf16_f32 v76, v88, v89
	v_cvt_pk_bf16_f32 v77, v90, v91
	v_cvt_pk_bf16_f32 v78, v92, v93
	v_cvt_pk_bf16_f32 v79, v94, v95
	v_cvt_pk_bf16_f32 v108, v120, v121
	v_cvt_pk_bf16_f32 v109, v122, v123
	v_cvt_pk_bf16_f32 v110, v124, v125
	v_cvt_pk_bf16_f32 v111, v126, v127
	s_waitcnt lgkmcnt(1)
	v_mfma_f32_32x32x16_bf16 v[0:15], v[200:203], v[76:79], v[0:15]
	v_mfma_f32_32x32x16_bf16 v[32:47], v[200:203], v[108:111], v[32:47]
	s_waitcnt lgkmcnt(0)
	v_mfma_f32_32x32x16_bf16 v[16:31], v[204:207], v[76:79], v[16:31]
	v_mfma_f32_32x32x16_bf16 v[48:63], v[204:207], v[108:111], v[48:63]
	s_add_u32 s68, s68, 1
	s_waitcnt lgkmcnt(0)
	s_barrier
	ds_read_b128 v[192:195], v128 offset:0
	ds_read_b128 v[196:199], v128 offset:6656
	ds_read_b128 v[200:203], v128 offset:32
	ds_read_b128 v[204:207], v128 offset:6688
	s_waitcnt lgkmcnt(3)
	v_mfma_f32_32x32x16_bf16 v[64:79], v[192:195], v[144:147], v[208:223]
	v_mfma_f32_32x32x16_bf16 v[96:111], v[192:195], v[168:171], v[208:223]
	ds_read_b128 v[192:195], v128 offset:64
	s_waitcnt lgkmcnt(3)
	v_mfma_f32_32x32x16_bf16 v[80:95], v[196:199], v[144:147], v[208:223]
	v_mfma_f32_32x32x16_bf16 v[112:127], v[196:199], v[168:171], v[208:223]
	ds_read_b128 v[196:199], v128 offset:6720
	s_waitcnt lgkmcnt(3)
	v_mfma_f32_32x32x16_bf16 v[64:79], v[200:203], v[148:151], v[64:79]
	v_mfma_f32_32x32x16_bf16 v[96:111], v[200:203], v[172:175], v[96:111]
	ds_read_b128 v[200:203], v128 offset:96
	s_waitcnt lgkmcnt(3)
	v_mfma_f32_32x32x16_bf16 v[80:95], v[204:207], v[148:151], v[80:95]
	v_mfma_f32_32x32x16_bf16 v[112:127], v[204:207], v[172:175], v[112:127]
	ds_read_b128 v[204:207], v128 offset:6752
	s_waitcnt lgkmcnt(3)
	v_mfma_f32_32x32x16_bf16 v[64:79], v[192:195], v[152:155], v[64:79]
	v_mfma_f32_32x32x16_bf16 v[96:111], v[192:195], v[176:179], v[96:111]
	ds_read_b128 v[192:195], v128 offset:128
	s_waitcnt lgkmcnt(3)
	v_mfma_f32_32x32x16_bf16 v[80:95], v[196:199], v[152:155], v[80:95]
	v_mfma_f32_32x32x16_bf16 v[112:127], v[196:199], v[176:179], v[112:127]
	ds_read_b128 v[196:199], v128 offset:6784
	s_waitcnt lgkmcnt(3)
	v_mfma_f32_32x32x16_bf16 v[64:79], v[200:203], v[156:159], v[64:79]
	v_mfma_f32_32x32x16_bf16 v[96:111], v[200:203], v[180:183], v[96:111]
	ds_read_b128 v[200:203], v128 offset:160
	s_waitcnt lgkmcnt(3)
	v_mfma_f32_32x32x16_bf16 v[80:95], v[204:207], v[156:159], v[80:95]
	v_mfma_f32_32x32x16_bf16 v[112:127], v[204:207], v[180:183], v[112:127]
	ds_read_b128 v[204:207], v128 offset:6816
	s_waitcnt lgkmcnt(3)
	v_mfma_f32_32x32x16_bf16 v[64:79], v[192:195], v[160:163], v[64:79]
	v_mfma_f32_32x32x16_bf16 v[96:111], v[192:195], v[184:187], v[96:111]
	s_waitcnt lgkmcnt(2)
	v_mfma_f32_32x32x16_bf16 v[80:95], v[196:199], v[160:163], v[80:95]
	v_mfma_f32_32x32x16_bf16 v[112:127], v[196:199], v[184:187], v[112:127]
	s_waitcnt lgkmcnt(1)
	v_mfma_f32_32x32x16_bf16 v[64:79], v[200:203], v[164:167], v[64:79]
	v_mfma_f32_32x32x16_bf16 v[96:111], v[200:203], v[188:191], v[96:111]
	s_waitcnt lgkmcnt(0)
	v_mfma_f32_32x32x16_bf16 v[80:95], v[204:207], v[164:167], v[80:95]
	v_mfma_f32_32x32x16_bf16 v[112:127], v[204:207], v[188:191], v[112:127]
	s_cmp_lt_u32 s68, 68
	s_cbranch_scc1 .Lat2_loop_m
; DI unsigned pack2(float lo, float hi) { f32x2_t v = {lo, hi}; bf16x2_t r = __builtin_convertvector(v, bf16x2_t); return __builtin_bit_cast(unsigned, r); }
; DI float xhalf_sum(float x) { auto r = __builtin_amdgcn_permlane32_swap(__float_as_uint(x), __float_as_uint(x), false, false); return __uint_as_float(r[0]) + __uint_as_float(r[1]); }
; template <int DQK>
; DI void attn_item(const bf16_t* __restrict__ Q, const bf16_t* __restrict__ Kp, const bf16_t* __restrict__ Vt, int q0, int nkeys,
;                   bf16_t* __restrict__ mix, int colbase, int b, char* smem) {
;     ...
;   l = xhalf_sum(l);
;   const float inv = 1.0f / l;
;   const int kp = q0 + wave * 32 + r;
;   bf16_t* orow = mix + (size_t)row_of(b, kp) * D + colbase;
; #pragma unroll
;   for (int g = 0; g < 4; ++g) {
;     uint2 w0, w1;
;     w0.x = pack2(o0[4 * g] * inv, o0[4 * g + 1] * inv); w0.y = pack2(o0[4 * g + 2] * inv, o0[4 * g + 3] * inv);
;     w1.x = pack2(o1[4 * g] * inv, o1[4 * g + 1] * inv); w1.y = pack2(o1[4 * g + 2] * inv, o1[4 * g + 3] * inv);
;     *(uint2*)(orow + 8 * g + 4 * h) = w0;
;     *(uint2*)(orow + 32 + 8 * g + 4 * h) = w1;
;   }
	s_waitcnt vmcnt(0)
	s_nop 7
	s_nop 7
	v_add_f32_e32 v244, v244, v245
	v_add_f32_e32 v246, v246, v247
	v_mov_b32_e32 v248, v244
	v_mov_b32_e32 v249, v246
	s_nop 1
	v_permlane32_swap_b32_e32 v244, v248
	v_permlane32_swap_b32_e32 v246, v249
	v_add_f32_e32 v244, v244, v248
	v_add_f32_e32 v246, v246, v249
	v_mov_b32_e32 v248, 0
	v_fmac_f32_e32 v248, 0, v0
	v_fmac_f32_e32 v248, 0, v1
	v_fmac_f32_e32 v248, 0, v2
	v_fmac_f32_e32 v248, 0, v3
	v_fmac_f32_e32 v248, 0, v4
	v_fmac_f32_e32 v248, 0, v5
	v_fmac_f32_e32 v248, 0, v6
	v_fmac_f32_e32 v248, 0, v7
	v_fmac_f32_e32 v248, 0, v8
	v_fmac_f32_e32 v248, 0, v9
	v_fmac_f32_e32 v248, 0, v10
	v_fmac_f32_e32 v248, 0, v11
	v_fmac_f32_e32 v248, 0, v12
	v_fmac_f32_e32 v248, 0, v13
	v_fmac_f32_e32 v248, 0, v14
	v_fmac_f32_e32 v248, 0, v15
	v_fmac_f32_e32 v248, 0, v16
	v_fmac_f32_e32 v248, 0, v17
	v_fmac_f32_e32 v248, 0, v18
	v_fmac_f32_e32 v248, 0, v19
	v_fmac_f32_e32 v248, 0, v20
	v_fmac_f32_e32 v248, 0, v21
	v_fmac_f32_e32 v248, 0, v22
	v_fmac_f32_e32 v248, 0, v23
	v_fmac_f32_e32 v248, 0, v24
	v_fmac_f32_e32 v248, 0, v25
	v_fmac_f32_e32 v248, 0, v26
	v_fmac_f32_e32 v248, 0, v27
	v_fmac_f32_e32 v248, 0, v28
	v_fmac_f32_e32 v248, 0, v29
	v_fmac_f32_e32 v248, 0, v30
	v_fmac_f32_e32 v248, 0, v31
	v_fmac_f32_e32 v248, 0, v32
	v_fmac_f32_e32 v248, 0, v33
	v_fmac_f32_e32 v248, 0, v34
	v_fmac_f32_e32 v248, 0, v35
	v_fmac_f32_e32 v248, 0, v36
	v_fmac_f32_e32 v248, 0, v37
	v_fmac_f32_e32 v248, 0, v38
	v_fmac_f32_e32 v248, 0, v39
	v_fmac_f32_e32 v248, 0, v40
	v_fmac_f32_e32 v248, 0, v41
	v_fmac_f32_e32 v248, 0, v42
	v_fmac_f32_e32 v248, 0, v43
	v_fmac_f32_e32 v248, 0, v44
	v_fmac_f32_e32 v248, 0, v45
	v_fmac_f32_e32 v248, 0, v46
	v_fmac_f32_e32 v248, 0, v47
	v_fmac_f32_e32 v248, 0, v48
	v_fmac_f32_e32 v248, 0, v49
	v_fmac_f32_e32 v248, 0, v50
	v_fmac_f32_e32 v248, 0, v51
	v_fmac_f32_e32 v248, 0, v52
	v_fmac_f32_e32 v248, 0, v53
	v_fmac_f32_e32 v248, 0, v54
	v_fmac_f32_e32 v248, 0, v55
	v_fmac_f32_e32 v248, 0, v56
	v_fmac_f32_e32 v248, 0, v57
	v_fmac_f32_e32 v248, 0, v58
	v_fmac_f32_e32 v248, 0, v59
	v_fmac_f32_e32 v248, 0, v60
	v_fmac_f32_e32 v248, 0, v61
	v_fmac_f32_e32 v248, 0, v62
	v_fmac_f32_e32 v248, 0, v63
	v_mov_b32_e32 v249, 0x71800000
	v_mov_b32_e32 v250, 0x21800000
	v_cmp_neq_f32_e32 vcc, 0, v248
	s_mov_b64 s[44:45], vcc
	v_cmp_nlt_f32_e32 vcc, v244, v249
	s_or_b64 s[44:45], vcc, s[44:45]
	v_cmp_ngt_f32_e32 vcc, v244, v250
	s_or_b64 s[44:45], vcc, s[44:45]
	v_cmp_nlt_f32_e32 vcc, v246, v249
	s_or_b64 s[44:45], vcc, s[44:45]
	v_cmp_ngt_f32_e32 vcc, v246, v250
	s_or_b64 s[44:45], vcc, s[44:45]
	s_cmp_lg_u64 s[44:45], 0
	s_cselect_b32 s0, 1, 0
	v_mov_b32_e32 v250, s0
	s_lshl_b32 s1, s57, 2
	s_add_u32 s1, s1, 0x13400
	v_mov_b32_e32 v251, s1
	v_mov_b32_e32 v252, 0x13400
	ds_write_b32 v251, v250
	s_waitcnt lgkmcnt(0)
	s_barrier
	ds_read_b128 v[192:195], v252
	s_waitcnt lgkmcnt(0)
	v_or3_b32 v250, v192, v193, v194
	v_or_b32_e32 v250, v250, v195
	s_nop 0
	v_readfirstlane_b32 s0, v250
	s_nop 3
	s_cmp_eq_u32 s0, 0
	s_cbranch_scc0 .Lat2_fallback
	v_rcp_f32_e32 v248, v244
	v_rcp_f32_e32 v249, v246
	s_nop 0
	v_mul_f32_e32 v64, v0, v248
	v_mul_f32_e32 v65, v1, v248
	v_mul_f32_e32 v66, v2, v248
	v_mul_f32_e32 v67, v3, v248
	v_cvt_pk_bf16_f32 v192, v64, v65
	v_cvt_pk_bf16_f32 v193, v66, v67
	global_store_dwordx2 v141, v[192:193], s[72:73] offset:0
	v_mul_f32_e32 v64, v16, v248
	v_mul_f32_e32 v65, v17, v248
	v_mul_f32_e32 v66, v18, v248
	v_mul_f32_e32 v67, v19, v248
	v_cvt_pk_bf16_f32 v194, v64, v65
	v_cvt_pk_bf16_f32 v195, v66, v67
	global_store_dwordx2 v142, v[194:195], s[72:73] offset:0
	v_mul_f32_e32 v64, v4, v248
	v_mul_f32_e32 v65, v5, v248
	v_mul_f32_e32 v66, v6, v248
	v_mul_f32_e32 v67, v7, v248
	v_cvt_pk_bf16_f32 v196, v64, v65
	v_cvt_pk_bf16_f32 v197, v66, v67
	global_store_dwordx2 v141, v[196:197], s[72:73] offset:16
	v_mul_f32_e32 v64, v20, v248
	v_mul_f32_e32 v65, v21, v248
	v_mul_f32_e32 v66, v22, v248
	v_mul_f32_e32 v67, v23, v248
	v_cvt_pk_bf16_f32 v198, v64, v65
	v_cvt_pk_bf16_f32 v199, v66, v67
	global_store_dwordx2 v142, v[198:199], s[72:73] offset:16
	v_mul_f32_e32 v64, v8, v248
	v_mul_f32_e32 v65, v9, v248
	v_mul_f32_e32 v66, v10, v248
	v_mul_f32_e32 v67, v11, v248
	v_cvt_pk_bf16_f32 v200, v64, v65
	v_cvt_pk_bf16_f32 v201, v66, v67
	global_store_dwordx2 v141, v[200:201], s[72:73] offset:32
	v_mul_f32_e32 v64, v24, v248
	v_mul_f32_e32 v65, v25, v248
	v_mul_f32_e32 v66, v26, v248
	v_mul_f32_e32 v67, v27, v248
	v_cvt_pk_bf16_f32 v202, v64, v65
	v_cvt_pk_bf16_f32 v203, v66, v67
	global_store_dwordx2 v142, v[202:203], s[72:73] offset:32
	v_mul_f32_e32 v64, v12, v248
	v_mul_f32_e32 v65, v13, v248
	v_mul_f32_e32 v66, v14, v248
	v_mul_f32_e32 v67, v15, v248
	v_cvt_pk_bf16_f32 v204, v64, v65
	v_cvt_pk_bf16_f32 v205, v66, v67
	global_store_dwordx2 v141, v[204:205], s[72:73] offset:48
	v_mul_f32_e32 v64, v28, v248
	v_mul_f32_e32 v65, v29, v248
	v_mul_f32_e32 v66, v30, v248
	v_mul_f32_e32 v67, v31, v248
	v_cvt_pk_bf16_f32 v206, v64, v65
	v_cvt_pk_bf16_f32 v207, v66, v67
	global_store_dwordx2 v142, v[206:207], s[72:73] offset:48
	v_mul_f32_e32 v64, v32, v249
	v_mul_f32_e32 v65, v33, v249
	v_mul_f32_e32 v66, v34, v249
	v_mul_f32_e32 v67, v35, v249
	v_cvt_pk_bf16_f32 v192, v64, v65
	v_cvt_pk_bf16_f32 v193, v66, v67
	global_store_dwordx2 v141, v[192:193], s[76:77] offset:0
	v_mul_f32_e32 v64, v48, v249
	v_mul_f32_e32 v65, v49, v249
	v_mul_f32_e32 v66, v50, v249
	v_mul_f32_e32 v67, v51, v249
	v_cvt_pk_bf16_f32 v194, v64, v65
	v_cvt_pk_bf16_f32 v195, v66, v67
	global_store_dwordx2 v142, v[194:195], s[76:77] offset:0
	v_mul_f32_e32 v64, v36, v249
	v_mul_f32_e32 v65, v37, v249
	v_mul_f32_e32 v66, v38, v249
	v_mul_f32_e32 v67, v39, v249
	v_cvt_pk_bf16_f32 v196, v64, v65
	v_cvt_pk_bf16_f32 v197, v66, v67
	global_store_dwordx2 v141, v[196:197], s[76:77] offset:16
	v_mul_f32_e32 v64, v52, v249
	v_mul_f32_e32 v65, v53, v249
	v_mul_f32_e32 v66, v54, v249
	v_mul_f32_e32 v67, v55, v249
	v_cvt_pk_bf16_f32 v198, v64, v65
	v_cvt_pk_bf16_f32 v199, v66, v67
	global_store_dwordx2 v142, v[198:199], s[76:77] offset:16
	v_mul_f32_e32 v64, v40, v249
	v_mul_f32_e32 v65, v41, v249
	v_mul_f32_e32 v66, v42, v249
	v_mul_f32_e32 v67, v43, v249
	v_cvt_pk_bf16_f32 v200, v64, v65
	v_cvt_pk_bf16_f32 v201, v66, v67
	global_store_dwordx2 v141, v[200:201], s[76:77] offset:32
	v_mul_f32_e32 v64, v56, v249
	v_mul_f32_e32 v65, v57, v249
	v_mul_f32_e32 v66, v58, v249
	v_mul_f32_e32 v67, v59, v249
	v_cvt_pk_bf16_f32 v202, v64, v65
	v_cvt_pk_bf16_f32 v203, v66, v67
	global_store_dwordx2 v142, v[202:203], s[76:77] offset:32
	v_mul_f32_e32 v64, v44, v249
	v_mul_f32_e32 v65, v45, v249
	v_mul_f32_e32 v66, v46, v249
	v_mul_f32_e32 v67, v47, v249
	v_cvt_pk_bf16_f32 v204, v64, v65
	v_cvt_pk_bf16_f32 v205, v66, v67
	global_store_dwordx2 v141, v[204:205], s[76:77] offset:48
	v_mul_f32_e32 v64, v60, v249
	v_mul_f32_e32 v65, v61, v249
	v_mul_f32_e32 v66, v62, v249
	v_mul_f32_e32 v67, v63, v249
	v_cvt_pk_bf16_f32 v206, v64, v65
	v_cvt_pk_bf16_f32 v207, v66, v67
	global_store_dwordx2 v142, v[206:207], s[76:77] offset:48
